# grid barrier P2->P3 replaced by early per-XCC arrival after ret_kv (writeback by the XCC's last arriver) + local wait; guarded by the runtime placement flag
# speedup vs baseline: 1.0078x; 1.0078x over previous
.LBB0_384:
	s_cmp_lg_u32 s98, 0
	s_cbranch_scc0 .Lrk_noarr
	s_waitcnt vmcnt(0)
	s_barrier
	v_readlane_b32 s99, v254, 25
	v_readlane_b32 s100, v254, 24
	s_nop 3
	s_cmp_lg_u32 s99, 0
	s_cbranch_scc1 .Lrk_noarr
	s_lshl_b32 s100, s100, 8
	s_add_i32 s100, s100, 0xfa0c100
	v_mov_b32_e32 v0, s100
	v_mov_b32_e32 v1, 1
	s_mov_b64 s[100:101], exec
	s_mov_b64 exec, 1
	v_mov_b32_e32 v3, 0x21000
	ds_read_b32 v3, v3
	global_atomic_add v2, v0, v1, s[74:75] sc0
	s_waitcnt vmcnt(0) lgkmcnt(0)
	v_add_u32_e32 v2, 1, v2
	v_cmp_eq_u32_e32 vcc, v2, v3
	s_cbranch_vccz .Lrk_arrd
	buffer_wbl2 sc1
	s_waitcnt vmcnt(0)
	v_mov_b32_e32 v0, 0xfa0e000
	global_atomic_add v0, v1, s[74:75]
.Lrk_arrd:
	s_mov_b64 exec, s[100:101]

.LBB0_469:
	s_waitcnt vmcnt(0)
	v_readlane_b32 s66, v254, 22
	v_readlane_b32 s67, v254, 23
	v_readlane_b32 s72, v255, 2
	v_readlane_b32 s52, v254, 55
	s_and_b64 vcc, exec, s[66:67]
	v_readlane_b32 s70, v255, 10
	v_readlane_b32 s73, v255, 3
	v_readlane_b32 s53, v254, 56
	v_readlane_b32 s42, v254, 50
	s_waitcnt vmcnt(63) expcnt(7) lgkmcnt(15)
	s_barrier
	v_readlane_b32 s43, v254, 51
	s_cbranch_vccnz .LBB0_523
	s_cmp_lg_u32 s98, 0
	s_cbranch_scc0 .Lb3_orig
	s_mov_b64 s[100:101], exec
	s_mov_b64 exec, 1
	v_mov_b32_e32 v0, 0x21004
	ds_read_b32 v1, v0
	v_mov_b32_e32 v0, 0xfa0e000
	s_mov_b32 s99, 0
	s_waitcnt lgkmcnt(0)
.Lb3_poll:
	global_load_dword v2, v0, s[74:75] sc1
	s_waitcnt vmcnt(0)
	v_cmp_ge_u32_e32 vcc, v2, v1
	s_cbranch_vccnz .Lb3_done
	s_sleep 1
	s_add_i32 s99, s99, 1
	s_cmp_lt_u32 s99, 0x100000
	s_cbranch_scc1 .Lb3_poll
.Lb3_done:
	buffer_inv sc1
	s_waitcnt vmcnt(0)
	s_mov_b64 exec, s[100:101]
	s_branch .LBB0_523
.Lb3_orig:
	v_mbcnt_lo_u32_b32 v0, -1, 0
	v_mbcnt_hi_u32_b32 v0, -1, v0
	s_nop 0
	v_cmp_eq_u32_e32 vcc, 0, v0
	s_and_saveexec_b64 s[0:1], vcc
	s_cbranch_execz .LBB0_522
	s_add_i32 s2, 0, 0x21000
	v_mov_b32_e32 v0, s2
	s_waitcnt vmcnt(0) expcnt(0) lgkmcnt(0)
	ds_read_b32 v2, v0
	s_add_i32 s2, 0, 0x21004
	v_mov_b32_e32 v0, s2
	ds_read_b32 v0, v0
	s_waitcnt lgkmcnt(1)
	v_cmp_ne_u32_e32 vcc, 0, v2
	s_cbranch_vccnz .LBB0_486
	s_add_u32 s4, s74, 0xfa00200
	s_addc_u32 s5, s75, 0
	s_add_u32 s6, s74, 0xfa00400
	s_addc_u32 s7, s75, 0
	s_add_u32 s8, s74, 0xfa00500
	s_addc_u32 s9, s75, 0
	s_add_u32 s10, s74, 0xfa00600
	s_addc_u32 s11, s75, 0
	s_add_u32 s12, s74, 0xfa00700
	s_addc_u32 s13, s75, 0
	s_add_u32 s14, s74, 0xfa00800
	s_addc_u32 s15, s75, 0
	s_add_u32 s16, s74, 0xfa00900
	s_addc_u32 s17, s75, 0
	s_add_u32 s18, s74, 0xfa00a00
	s_addc_u32 s19, s75, 0
	s_add_u32 s20, s74, 0xfa00b00
	s_addc_u32 s21, s75, 0
	s_add_u32 s22, s74, 0xfa00c00
	s_addc_u32 s23, s75, 0
	s_add_u32 s24, s74, 0xfa00d00
	s_addc_u32 s25, s75, 0
	s_add_u32 s26, s74, 0xfa00e00
	s_addc_u32 s27, s75, 0
	s_add_u32 s28, s74, 0xfa00f00
	s_addc_u32 s29, s75, 0
	s_add_u32 s30, s74, 0xfa01000
	s_addc_u32 s31, s75, 0
	s_add_u32 s34, s74, 0xfa01100
	s_addc_u32 s35, s75, 0
	s_add_u32 s36, s74, 0xfa01200
	v_readlane_b32 s2, v254, 4
	s_addc_u32 s37, s75, 0
	s_mul_i32 s2, s79, s2
	s_add_u32 s38, s74, 0xfa01300
	s_mul_i32 s2, s2, s78
	s_addc_u32 s39, s75, 0
	s_mov_b32 s3, 1
	v_mov_b32_e32 v16, 0
	s_branch .LBB0_474
